# HGRN2 pass-2 scan: two 16-chunk load batches in flight with counted waits (no per-batch drain of loads and stores)
# speedup vs baseline: 1.0074x; 1.0074x over previous
; __device__ __forceinline__ unsigned cvt_pk_bf16(float lo, float hi) { const f32x2cv v = {lo, hi}; const bf16x2cv b = __builtin_convertvector(v, bf16x2cv); return __builtin_bit_cast(unsigned, b); }
; __device__ __forceinline__ float bflo(unsigned w) { return __uint_as_float(w << 16); }
; __device__ __forceinline__ float bfhi(unsigned w) { return __uint_as_float(w & 0xffff0000u); }
; __device__ __forceinline__ void hgrn_pass2(Frame& F) {
;     ...
;     for (int item = F.vcu * 256 + F.tid; item < 8 * 128 * 64; item += F.G * 256) {
;         const int bh = item >> 13, rem = item & 8191;
;         unsigned* up = (unsigned*)((bf16*)F.out + (size_t)bh * 128 * 16384) + rem; const float2* dp = (const float2*)((const float*)(F.ws + WS_HD) + (size_t)bh * 128 * 128) + (rem & 63);
;         float s0 = 0.f, s1 = 0.f;
; #pragma unroll 32
;         for (int c = 0; c < 128; ++c) { const unsigned u = up[(size_t)c * 8192]; const float2 d = dp[c * 64];
;             up[(size_t)c * 8192] = cvt_pk_bf16(s0, s1);
;             s0 = d.x * s0 + bflo(u); s1 = d.y * s1 + bfhi(u); }
.LBB0_621:
	v_ashrrev_i32_e32 v2, 13, v10
	v_and_b32_e32 v3, 0x1fff, v11
	v_lshlrev_b32_e32 v4, 22, v2
	v_lshl_or_b32 v6, v3, 2, v4
	v_lshlrev_b32_e32 v4, 16, v2
	v_add_u32_e32 v12, v4, v192
	v_add_u32_e32 v12, 0x3900000, v12
	v_mov_b32_e32 v14, v6
	v_mov_b32_e32 v8, 0
	v_mov_b32_e32 v9, 0
	global_load_dword v32, v6, s[8:9]
	global_load_dwordx2 v[64:65], v12, s[10:11]
	v_add_u32_e32 v6, 0x8000, v6
	v_add_u32_e32 v12, 0x200, v12
	global_load_dword v33, v6, s[8:9]
	global_load_dwordx2 v[66:67], v12, s[10:11]
	v_add_u32_e32 v6, 0x8000, v6
	v_add_u32_e32 v12, 0x200, v12
	global_load_dword v34, v6, s[8:9]
	global_load_dwordx2 v[68:69], v12, s[10:11]
	v_add_u32_e32 v6, 0x8000, v6
	v_add_u32_e32 v12, 0x200, v12
	global_load_dword v35, v6, s[8:9]
	global_load_dwordx2 v[70:71], v12, s[10:11]
	v_add_u32_e32 v6, 0x8000, v6
	v_add_u32_e32 v12, 0x200, v12
	global_load_dword v36, v6, s[8:9]
	global_load_dwordx2 v[72:73], v12, s[10:11]
	v_add_u32_e32 v6, 0x8000, v6
	v_add_u32_e32 v12, 0x200, v12
	global_load_dword v37, v6, s[8:9]
	global_load_dwordx2 v[74:75], v12, s[10:11]
	v_add_u32_e32 v6, 0x8000, v6
	v_add_u32_e32 v12, 0x200, v12
	global_load_dword v38, v6, s[8:9]
	global_load_dwordx2 v[76:77], v12, s[10:11]
	v_add_u32_e32 v6, 0x8000, v6
	v_add_u32_e32 v12, 0x200, v12
	global_load_dword v39, v6, s[8:9]
	global_load_dwordx2 v[78:79], v12, s[10:11]
	v_add_u32_e32 v6, 0x8000, v6
	v_add_u32_e32 v12, 0x200, v12
	global_load_dword v40, v6, s[8:9]
	global_load_dwordx2 v[80:81], v12, s[10:11]
	v_add_u32_e32 v6, 0x8000, v6
	v_add_u32_e32 v12, 0x200, v12
	global_load_dword v41, v6, s[8:9]
	global_load_dwordx2 v[82:83], v12, s[10:11]
	v_add_u32_e32 v6, 0x8000, v6
	v_add_u32_e32 v12, 0x200, v12
	global_load_dword v42, v6, s[8:9]
	global_load_dwordx2 v[84:85], v12, s[10:11]
	v_add_u32_e32 v6, 0x8000, v6
	v_add_u32_e32 v12, 0x200, v12
	global_load_dword v43, v6, s[8:9]
	global_load_dwordx2 v[86:87], v12, s[10:11]
	v_add_u32_e32 v6, 0x8000, v6
	v_add_u32_e32 v12, 0x200, v12
	global_load_dword v44, v6, s[8:9]
	global_load_dwordx2 v[88:89], v12, s[10:11]
	v_add_u32_e32 v6, 0x8000, v6
	v_add_u32_e32 v12, 0x200, v12
	global_load_dword v45, v6, s[8:9]
	global_load_dwordx2 v[90:91], v12, s[10:11]
	v_add_u32_e32 v6, 0x8000, v6
	v_add_u32_e32 v12, 0x200, v12
	global_load_dword v46, v6, s[8:9]
	global_load_dwordx2 v[92:93], v12, s[10:11]
	v_add_u32_e32 v6, 0x8000, v6
	v_add_u32_e32 v12, 0x200, v12
	global_load_dword v47, v6, s[8:9]
	global_load_dwordx2 v[94:95], v12, s[10:11]
	v_add_u32_e32 v6, 0x8000, v6
	v_add_u32_e32 v12, 0x200, v12
	global_load_dword v48, v6, s[8:9]
	global_load_dwordx2 v[96:97], v12, s[10:11]
	v_add_u32_e32 v6, 0x8000, v6
	v_add_u32_e32 v12, 0x200, v12
	global_load_dword v49, v6, s[8:9]
	global_load_dwordx2 v[98:99], v12, s[10:11]
	v_add_u32_e32 v6, 0x8000, v6
	v_add_u32_e32 v12, 0x200, v12
	global_load_dword v50, v6, s[8:9]
	global_load_dwordx2 v[100:101], v12, s[10:11]
	v_add_u32_e32 v6, 0x8000, v6
	v_add_u32_e32 v12, 0x200, v12
	global_load_dword v51, v6, s[8:9]
	global_load_dwordx2 v[102:103], v12, s[10:11]
	v_add_u32_e32 v6, 0x8000, v6
	v_add_u32_e32 v12, 0x200, v12
	global_load_dword v52, v6, s[8:9]
	global_load_dwordx2 v[104:105], v12, s[10:11]
	v_add_u32_e32 v6, 0x8000, v6
	v_add_u32_e32 v12, 0x200, v12
	global_load_dword v53, v6, s[8:9]
	global_load_dwordx2 v[106:107], v12, s[10:11]
	v_add_u32_e32 v6, 0x8000, v6
	v_add_u32_e32 v12, 0x200, v12
	global_load_dword v54, v6, s[8:9]
	global_load_dwordx2 v[108:109], v12, s[10:11]
	v_add_u32_e32 v6, 0x8000, v6
	v_add_u32_e32 v12, 0x200, v12
	global_load_dword v55, v6, s[8:9]
	global_load_dwordx2 v[110:111], v12, s[10:11]
	v_add_u32_e32 v6, 0x8000, v6
	v_add_u32_e32 v12, 0x200, v12
	global_load_dword v56, v6, s[8:9]
	global_load_dwordx2 v[112:113], v12, s[10:11]
	v_add_u32_e32 v6, 0x8000, v6
	v_add_u32_e32 v12, 0x200, v12
	global_load_dword v57, v6, s[8:9]
	global_load_dwordx2 v[114:115], v12, s[10:11]
	v_add_u32_e32 v6, 0x8000, v6
	v_add_u32_e32 v12, 0x200, v12
	global_load_dword v58, v6, s[8:9]
	global_load_dwordx2 v[116:117], v12, s[10:11]
	v_add_u32_e32 v6, 0x8000, v6
	v_add_u32_e32 v12, 0x200, v12
	global_load_dword v59, v6, s[8:9]
	global_load_dwordx2 v[118:119], v12, s[10:11]
	v_add_u32_e32 v6, 0x8000, v6
	v_add_u32_e32 v12, 0x200, v12
	global_load_dword v60, v6, s[8:9]
	global_load_dwordx2 v[120:121], v12, s[10:11]
	v_add_u32_e32 v6, 0x8000, v6
	v_add_u32_e32 v12, 0x200, v12
	global_load_dword v61, v6, s[8:9]
	global_load_dwordx2 v[122:123], v12, s[10:11]
	v_add_u32_e32 v6, 0x8000, v6
	v_add_u32_e32 v12, 0x200, v12
	global_load_dword v62, v6, s[8:9]
	global_load_dwordx2 v[124:125], v12, s[10:11]
	v_add_u32_e32 v6, 0x8000, v6
	v_add_u32_e32 v12, 0x200, v12
	global_load_dword v63, v6, s[8:9]
	global_load_dwordx2 v[126:127], v12, s[10:11]
	v_add_u32_e32 v6, 0x8000, v6
	v_add_u32_e32 v12, 0x200, v12
	s_waitcnt vmcnt(32)
; __device__ __forceinline__ unsigned cvt_pk_bf16(float lo, float hi) { const f32x2cv v = {lo, hi}; const bf16x2cv b = __builtin_convertvector(v, bf16x2cv); return __builtin_bit_cast(unsigned, b); }
; __device__ __forceinline__ float bflo(unsigned w) { return __uint_as_float(w << 16); }
; __device__ __forceinline__ float bfhi(unsigned w) { return __uint_as_float(w & 0xffff0000u); }
; __device__ __forceinline__ void hgrn_pass2(Frame& F) {
;     ...
;     for (int item = F.vcu * 256 + F.tid; item < 8 * 128 * 64; item += F.G * 256) {
;         const int bh = item >> 13, rem = item & 8191;
;         unsigned* up = (unsigned*)((bf16*)F.out + (size_t)bh * 128 * 16384) + rem; const float2* dp = (const float2*)((const float*)(F.ws + WS_HD) + (size_t)bh * 128 * 128) + (rem & 63);
;         float s0 = 0.f, s1 = 0.f;
; #pragma unroll 32
;         for (int c = 0; c < 128; ++c) { const unsigned u = up[(size_t)c * 8192]; const float2 d = dp[c * 64];
;             up[(size_t)c * 8192] = cvt_pk_bf16(s0, s1);
;             s0 = d.x * s0 + bflo(u); s1 = d.y * s1 + bfhi(u); }
	v_cvt_pk_bf16_f32 v16, v8, v9
	global_store_dword v14, v16, s[8:9]
	v_lshlrev_b32_e32 v18, 16, v32
	v_and_b32_e32 v19, 0xffff0000, v32
	v_pk_fma_f32 v[8:9], v[8:9], v[64:65], v[18:19]
	v_add_u32_e32 v14, 0x8000, v14
	v_cvt_pk_bf16_f32 v16, v8, v9
	global_store_dword v14, v16, s[8:9]
	v_lshlrev_b32_e32 v18, 16, v33
	v_and_b32_e32 v19, 0xffff0000, v33
	v_pk_fma_f32 v[8:9], v[8:9], v[66:67], v[18:19]
	v_add_u32_e32 v14, 0x8000, v14
	v_cvt_pk_bf16_f32 v16, v8, v9
	global_store_dword v14, v16, s[8:9]
	v_lshlrev_b32_e32 v18, 16, v34
	v_and_b32_e32 v19, 0xffff0000, v34
	v_pk_fma_f32 v[8:9], v[8:9], v[68:69], v[18:19]
	v_add_u32_e32 v14, 0x8000, v14
	v_cvt_pk_bf16_f32 v16, v8, v9
	global_store_dword v14, v16, s[8:9]
	v_lshlrev_b32_e32 v18, 16, v35
	v_and_b32_e32 v19, 0xffff0000, v35
	v_pk_fma_f32 v[8:9], v[8:9], v[70:71], v[18:19]
	v_add_u32_e32 v14, 0x8000, v14
	v_cvt_pk_bf16_f32 v16, v8, v9
	global_store_dword v14, v16, s[8:9]
	v_lshlrev_b32_e32 v18, 16, v36
	v_and_b32_e32 v19, 0xffff0000, v36
	v_pk_fma_f32 v[8:9], v[8:9], v[72:73], v[18:19]
	v_add_u32_e32 v14, 0x8000, v14
	v_cvt_pk_bf16_f32 v16, v8, v9
	global_store_dword v14, v16, s[8:9]
	v_lshlrev_b32_e32 v18, 16, v37
	v_and_b32_e32 v19, 0xffff0000, v37
	v_pk_fma_f32 v[8:9], v[8:9], v[74:75], v[18:19]
	v_add_u32_e32 v14, 0x8000, v14
	v_cvt_pk_bf16_f32 v16, v8, v9
	global_store_dword v14, v16, s[8:9]
	v_lshlrev_b32_e32 v18, 16, v38
	v_and_b32_e32 v19, 0xffff0000, v38
	v_pk_fma_f32 v[8:9], v[8:9], v[76:77], v[18:19]
	v_add_u32_e32 v14, 0x8000, v14
	v_cvt_pk_bf16_f32 v16, v8, v9
	global_store_dword v14, v16, s[8:9]
	v_lshlrev_b32_e32 v18, 16, v39
	v_and_b32_e32 v19, 0xffff0000, v39
	v_pk_fma_f32 v[8:9], v[8:9], v[78:79], v[18:19]
	v_add_u32_e32 v14, 0x8000, v14
	v_cvt_pk_bf16_f32 v16, v8, v9
	global_store_dword v14, v16, s[8:9]
	v_lshlrev_b32_e32 v18, 16, v40
	v_and_b32_e32 v19, 0xffff0000, v40
	v_pk_fma_f32 v[8:9], v[8:9], v[80:81], v[18:19]
	v_add_u32_e32 v14, 0x8000, v14
	v_cvt_pk_bf16_f32 v16, v8, v9
	global_store_dword v14, v16, s[8:9]
	v_lshlrev_b32_e32 v18, 16, v41
	v_and_b32_e32 v19, 0xffff0000, v41
	v_pk_fma_f32 v[8:9], v[8:9], v[82:83], v[18:19]
	v_add_u32_e32 v14, 0x8000, v14
	v_cvt_pk_bf16_f32 v16, v8, v9
	global_store_dword v14, v16, s[8:9]
	v_lshlrev_b32_e32 v18, 16, v42
	v_and_b32_e32 v19, 0xffff0000, v42
	v_pk_fma_f32 v[8:9], v[8:9], v[84:85], v[18:19]
	v_add_u32_e32 v14, 0x8000, v14
	v_cvt_pk_bf16_f32 v16, v8, v9
	global_store_dword v14, v16, s[8:9]
	v_lshlrev_b32_e32 v18, 16, v43
	v_and_b32_e32 v19, 0xffff0000, v43
	v_pk_fma_f32 v[8:9], v[8:9], v[86:87], v[18:19]
	v_add_u32_e32 v14, 0x8000, v14
	v_cvt_pk_bf16_f32 v16, v8, v9
	global_store_dword v14, v16, s[8:9]
	v_lshlrev_b32_e32 v18, 16, v44
	v_and_b32_e32 v19, 0xffff0000, v44
	v_pk_fma_f32 v[8:9], v[8:9], v[88:89], v[18:19]
	v_add_u32_e32 v14, 0x8000, v14
	v_cvt_pk_bf16_f32 v16, v8, v9
	global_store_dword v14, v16, s[8:9]
	v_lshlrev_b32_e32 v18, 16, v45
	v_and_b32_e32 v19, 0xffff0000, v45
	v_pk_fma_f32 v[8:9], v[8:9], v[90:91], v[18:19]
	v_add_u32_e32 v14, 0x8000, v14
	v_cvt_pk_bf16_f32 v16, v8, v9
	global_store_dword v14, v16, s[8:9]
	v_lshlrev_b32_e32 v18, 16, v46
	v_and_b32_e32 v19, 0xffff0000, v46
	v_pk_fma_f32 v[8:9], v[8:9], v[92:93], v[18:19]
	v_add_u32_e32 v14, 0x8000, v14
	v_cvt_pk_bf16_f32 v16, v8, v9
	global_store_dword v14, v16, s[8:9]
	v_lshlrev_b32_e32 v18, 16, v47
	v_and_b32_e32 v19, 0xffff0000, v47
	v_pk_fma_f32 v[8:9], v[8:9], v[94:95], v[18:19]
	v_add_u32_e32 v14, 0x8000, v14
	global_load_dword v128, v6, s[8:9]
	global_load_dwordx2 v[144:145], v12, s[10:11]
	v_add_u32_e32 v6, 0x8000, v6
	v_add_u32_e32 v12, 0x200, v12
	global_load_dword v129, v6, s[8:9]
	global_load_dwordx2 v[146:147], v12, s[10:11]
	v_add_u32_e32 v6, 0x8000, v6
	v_add_u32_e32 v12, 0x200, v12
	global_load_dword v130, v6, s[8:9]
	global_load_dwordx2 v[148:149], v12, s[10:11]
	v_add_u32_e32 v6, 0x8000, v6
	v_add_u32_e32 v12, 0x200, v12
	global_load_dword v131, v6, s[8:9]
	global_load_dwordx2 v[150:151], v12, s[10:11]
	v_add_u32_e32 v6, 0x8000, v6
	v_add_u32_e32 v12, 0x200, v12
	global_load_dword v132, v6, s[8:9]
	global_load_dwordx2 v[152:153], v12, s[10:11]
	v_add_u32_e32 v6, 0x8000, v6
	v_add_u32_e32 v12, 0x200, v12
	global_load_dword v133, v6, s[8:9]
	global_load_dwordx2 v[154:155], v12, s[10:11]
	v_add_u32_e32 v6, 0x8000, v6
	v_add_u32_e32 v12, 0x200, v12
	global_load_dword v134, v6, s[8:9]
	global_load_dwordx2 v[156:157], v12, s[10:11]
	v_add_u32_e32 v6, 0x8000, v6
	v_add_u32_e32 v12, 0x200, v12
	global_load_dword v135, v6, s[8:9]
	global_load_dwordx2 v[158:159], v12, s[10:11]
	v_add_u32_e32 v6, 0x8000, v6
	v_add_u32_e32 v12, 0x200, v12
	global_load_dword v136, v6, s[8:9]
	global_load_dwordx2 v[160:161], v12, s[10:11]
	v_add_u32_e32 v6, 0x8000, v6
	v_add_u32_e32 v12, 0x200, v12
	global_load_dword v137, v6, s[8:9]
	global_load_dwordx2 v[162:163], v12, s[10:11]
	v_add_u32_e32 v6, 0x8000, v6
	v_add_u32_e32 v12, 0x200, v12
	global_load_dword v138, v6, s[8:9]
	global_load_dwordx2 v[164:165], v12, s[10:11]
	v_add_u32_e32 v6, 0x8000, v6
	v_add_u32_e32 v12, 0x200, v12
	global_load_dword v139, v6, s[8:9]
	global_load_dwordx2 v[166:167], v12, s[10:11]
	v_add_u32_e32 v6, 0x8000, v6
	v_add_u32_e32 v12, 0x200, v12
	global_load_dword v140, v6, s[8:9]
	global_load_dwordx2 v[168:169], v12, s[10:11]
	v_add_u32_e32 v6, 0x8000, v6
	v_add_u32_e32 v12, 0x200, v12
	global_load_dword v141, v6, s[8:9]
	global_load_dwordx2 v[170:171], v12, s[10:11]
	v_add_u32_e32 v6, 0x8000, v6
	v_add_u32_e32 v12, 0x200, v12
	global_load_dword v142, v6, s[8:9]
	global_load_dwordx2 v[172:173], v12, s[10:11]
	v_add_u32_e32 v6, 0x8000, v6
	v_add_u32_e32 v12, 0x200, v12
	global_load_dword v143, v6, s[8:9]
	global_load_dwordx2 v[174:175], v12, s[10:11]
	v_add_u32_e32 v6, 0x8000, v6
	v_add_u32_e32 v12, 0x200, v12
	s_waitcnt vmcnt(48)
; __device__ __forceinline__ unsigned cvt_pk_bf16(float lo, float hi) { const f32x2cv v = {lo, hi}; const bf16x2cv b = __builtin_convertvector(v, bf16x2cv); return __builtin_bit_cast(unsigned, b); }
; __device__ __forceinline__ float bflo(unsigned w) { return __uint_as_float(w << 16); }
; __device__ __forceinline__ float bfhi(unsigned w) { return __uint_as_float(w & 0xffff0000u); }
; __device__ __forceinline__ void hgrn_pass2(Frame& F) {
;     ...
;     for (int item = F.vcu * 256 + F.tid; item < 8 * 128 * 64; item += F.G * 256) {
;         const int bh = item >> 13, rem = item & 8191;
;         unsigned* up = (unsigned*)((bf16*)F.out + (size_t)bh * 128 * 16384) + rem; const float2* dp = (const float2*)((const float*)(F.ws + WS_HD) + (size_t)bh * 128 * 128) + (rem & 63);
;         float s0 = 0.f, s1 = 0.f;
; #pragma unroll 32
;         for (int c = 0; c < 128; ++c) { const unsigned u = up[(size_t)c * 8192]; const float2 d = dp[c * 64];
;             up[(size_t)c * 8192] = cvt_pk_bf16(s0, s1);
;             s0 = d.x * s0 + bflo(u); s1 = d.y * s1 + bfhi(u); }
	v_cvt_pk_bf16_f32 v16, v8, v9
	global_store_dword v14, v16, s[8:9]
	v_lshlrev_b32_e32 v18, 16, v48
	v_and_b32_e32 v19, 0xffff0000, v48
	v_pk_fma_f32 v[8:9], v[8:9], v[96:97], v[18:19]
	v_add_u32_e32 v14, 0x8000, v14
	v_cvt_pk_bf16_f32 v16, v8, v9
	global_store_dword v14, v16, s[8:9]
	v_lshlrev_b32_e32 v18, 16, v49
	v_and_b32_e32 v19, 0xffff0000, v49
	v_pk_fma_f32 v[8:9], v[8:9], v[98:99], v[18:19]
	v_add_u32_e32 v14, 0x8000, v14
	v_cvt_pk_bf16_f32 v16, v8, v9
	global_store_dword v14, v16, s[8:9]
	v_lshlrev_b32_e32 v18, 16, v50
	v_and_b32_e32 v19, 0xffff0000, v50
	v_pk_fma_f32 v[8:9], v[8:9], v[100:101], v[18:19]
	v_add_u32_e32 v14, 0x8000, v14
	v_cvt_pk_bf16_f32 v16, v8, v9
	global_store_dword v14, v16, s[8:9]
	v_lshlrev_b32_e32 v18, 16, v51
	v_and_b32_e32 v19, 0xffff0000, v51
	v_pk_fma_f32 v[8:9], v[8:9], v[102:103], v[18:19]
	v_add_u32_e32 v14, 0x8000, v14
	v_cvt_pk_bf16_f32 v16, v8, v9
	global_store_dword v14, v16, s[8:9]
	v_lshlrev_b32_e32 v18, 16, v52
	v_and_b32_e32 v19, 0xffff0000, v52
	v_pk_fma_f32 v[8:9], v[8:9], v[104:105], v[18:19]
	v_add_u32_e32 v14, 0x8000, v14
	v_cvt_pk_bf16_f32 v16, v8, v9
	global_store_dword v14, v16, s[8:9]
	v_lshlrev_b32_e32 v18, 16, v53
	v_and_b32_e32 v19, 0xffff0000, v53
	v_pk_fma_f32 v[8:9], v[8:9], v[106:107], v[18:19]
	v_add_u32_e32 v14, 0x8000, v14
	v_cvt_pk_bf16_f32 v16, v8, v9
	global_store_dword v14, v16, s[8:9]
	v_lshlrev_b32_e32 v18, 16, v54
	v_and_b32_e32 v19, 0xffff0000, v54
	v_pk_fma_f32 v[8:9], v[8:9], v[108:109], v[18:19]
	v_add_u32_e32 v14, 0x8000, v14
	v_cvt_pk_bf16_f32 v16, v8, v9
	global_store_dword v14, v16, s[8:9]
	v_lshlrev_b32_e32 v18, 16, v55
	v_and_b32_e32 v19, 0xffff0000, v55
	v_pk_fma_f32 v[8:9], v[8:9], v[110:111], v[18:19]
	v_add_u32_e32 v14, 0x8000, v14
	v_cvt_pk_bf16_f32 v16, v8, v9
	global_store_dword v14, v16, s[8:9]
	v_lshlrev_b32_e32 v18, 16, v56
	v_and_b32_e32 v19, 0xffff0000, v56
	v_pk_fma_f32 v[8:9], v[8:9], v[112:113], v[18:19]
	v_add_u32_e32 v14, 0x8000, v14
	v_cvt_pk_bf16_f32 v16, v8, v9
	global_store_dword v14, v16, s[8:9]
	v_lshlrev_b32_e32 v18, 16, v57
	v_and_b32_e32 v19, 0xffff0000, v57
	v_pk_fma_f32 v[8:9], v[8:9], v[114:115], v[18:19]
	v_add_u32_e32 v14, 0x8000, v14
	v_cvt_pk_bf16_f32 v16, v8, v9
	global_store_dword v14, v16, s[8:9]
	v_lshlrev_b32_e32 v18, 16, v58
	v_and_b32_e32 v19, 0xffff0000, v58
	v_pk_fma_f32 v[8:9], v[8:9], v[116:117], v[18:19]
	v_add_u32_e32 v14, 0x8000, v14
	v_cvt_pk_bf16_f32 v16, v8, v9
	global_store_dword v14, v16, s[8:9]
	v_lshlrev_b32_e32 v18, 16, v59
	v_and_b32_e32 v19, 0xffff0000, v59
	v_pk_fma_f32 v[8:9], v[8:9], v[118:119], v[18:19]
	v_add_u32_e32 v14, 0x8000, v14
	v_cvt_pk_bf16_f32 v16, v8, v9
	global_store_dword v14, v16, s[8:9]
	v_lshlrev_b32_e32 v18, 16, v60
	v_and_b32_e32 v19, 0xffff0000, v60
	v_pk_fma_f32 v[8:9], v[8:9], v[120:121], v[18:19]
	v_add_u32_e32 v14, 0x8000, v14
	v_cvt_pk_bf16_f32 v16, v8, v9
	global_store_dword v14, v16, s[8:9]
	v_lshlrev_b32_e32 v18, 16, v61
	v_and_b32_e32 v19, 0xffff0000, v61
	v_pk_fma_f32 v[8:9], v[8:9], v[122:123], v[18:19]
	v_add_u32_e32 v14, 0x8000, v14
	v_cvt_pk_bf16_f32 v16, v8, v9
	global_store_dword v14, v16, s[8:9]
	v_lshlrev_b32_e32 v18, 16, v62
	v_and_b32_e32 v19, 0xffff0000, v62
	v_pk_fma_f32 v[8:9], v[8:9], v[124:125], v[18:19]
	v_add_u32_e32 v14, 0x8000, v14
	v_cvt_pk_bf16_f32 v16, v8, v9
	global_store_dword v14, v16, s[8:9]
	v_lshlrev_b32_e32 v18, 16, v63
	v_and_b32_e32 v19, 0xffff0000, v63
	v_pk_fma_f32 v[8:9], v[8:9], v[126:127], v[18:19]
	v_add_u32_e32 v14, 0x8000, v14
	global_load_dword v32, v6, s[8:9]
	global_load_dwordx2 v[64:65], v12, s[10:11]
	v_add_u32_e32 v6, 0x8000, v6
	v_add_u32_e32 v12, 0x200, v12
	global_load_dword v33, v6, s[8:9]
	global_load_dwordx2 v[66:67], v12, s[10:11]
	v_add_u32_e32 v6, 0x8000, v6
	v_add_u32_e32 v12, 0x200, v12
	global_load_dword v34, v6, s[8:9]
	global_load_dwordx2 v[68:69], v12, s[10:11]
	v_add_u32_e32 v6, 0x8000, v6
	v_add_u32_e32 v12, 0x200, v12
	global_load_dword v35, v6, s[8:9]
	global_load_dwordx2 v[70:71], v12, s[10:11]
	v_add_u32_e32 v6, 0x8000, v6
	v_add_u32_e32 v12, 0x200, v12
	global_load_dword v36, v6, s[8:9]
	global_load_dwordx2 v[72:73], v12, s[10:11]
	v_add_u32_e32 v6, 0x8000, v6
	v_add_u32_e32 v12, 0x200, v12
	global_load_dword v37, v6, s[8:9]
	global_load_dwordx2 v[74:75], v12, s[10:11]
	v_add_u32_e32 v6, 0x8000, v6
	v_add_u32_e32 v12, 0x200, v12
	global_load_dword v38, v6, s[8:9]
	global_load_dwordx2 v[76:77], v12, s[10:11]
	v_add_u32_e32 v6, 0x8000, v6
	v_add_u32_e32 v12, 0x200, v12
	global_load_dword v39, v6, s[8:9]
	global_load_dwordx2 v[78:79], v12, s[10:11]
	v_add_u32_e32 v6, 0x8000, v6
	v_add_u32_e32 v12, 0x200, v12
	global_load_dword v40, v6, s[8:9]
	global_load_dwordx2 v[80:81], v12, s[10:11]
	v_add_u32_e32 v6, 0x8000, v6
	v_add_u32_e32 v12, 0x200, v12
	global_load_dword v41, v6, s[8:9]
	global_load_dwordx2 v[82:83], v12, s[10:11]
	v_add_u32_e32 v6, 0x8000, v6
	v_add_u32_e32 v12, 0x200, v12
	global_load_dword v42, v6, s[8:9]
	global_load_dwordx2 v[84:85], v12, s[10:11]
	v_add_u32_e32 v6, 0x8000, v6
	v_add_u32_e32 v12, 0x200, v12
	global_load_dword v43, v6, s[8:9]
	global_load_dwordx2 v[86:87], v12, s[10:11]
	v_add_u32_e32 v6, 0x8000, v6
	v_add_u32_e32 v12, 0x200, v12
	global_load_dword v44, v6, s[8:9]
	global_load_dwordx2 v[88:89], v12, s[10:11]
	v_add_u32_e32 v6, 0x8000, v6
	v_add_u32_e32 v12, 0x200, v12
	global_load_dword v45, v6, s[8:9]
	global_load_dwordx2 v[90:91], v12, s[10:11]
	v_add_u32_e32 v6, 0x8000, v6
	v_add_u32_e32 v12, 0x200, v12
	global_load_dword v46, v6, s[8:9]
	global_load_dwordx2 v[92:93], v12, s[10:11]
	v_add_u32_e32 v6, 0x8000, v6
	v_add_u32_e32 v12, 0x200, v12
	global_load_dword v47, v6, s[8:9]
	global_load_dwordx2 v[94:95], v12, s[10:11]
	v_add_u32_e32 v6, 0x8000, v6
	v_add_u32_e32 v12, 0x200, v12
	s_waitcnt vmcnt(48)
; __device__ __forceinline__ unsigned cvt_pk_bf16(float lo, float hi) { const f32x2cv v = {lo, hi}; const bf16x2cv b = __builtin_convertvector(v, bf16x2cv); return __builtin_bit_cast(unsigned, b); }
; __device__ __forceinline__ float bflo(unsigned w) { return __uint_as_float(w << 16); }
; __device__ __forceinline__ float bfhi(unsigned w) { return __uint_as_float(w & 0xffff0000u); }
; __device__ __forceinline__ void hgrn_pass2(Frame& F) {
;     ...
;     for (int item = F.vcu * 256 + F.tid; item < 8 * 128 * 64; item += F.G * 256) {
;         const int bh = item >> 13, rem = item & 8191;
;         unsigned* up = (unsigned*)((bf16*)F.out + (size_t)bh * 128 * 16384) + rem; const float2* dp = (const float2*)((const float*)(F.ws + WS_HD) + (size_t)bh * 128 * 128) + (rem & 63);
;         float s0 = 0.f, s1 = 0.f;
; #pragma unroll 32
;         for (int c = 0; c < 128; ++c) { const unsigned u = up[(size_t)c * 8192]; const float2 d = dp[c * 64];
;             up[(size_t)c * 8192] = cvt_pk_bf16(s0, s1);
;             s0 = d.x * s0 + bflo(u); s1 = d.y * s1 + bfhi(u); }
	v_cvt_pk_bf16_f32 v16, v8, v9
	global_store_dword v14, v16, s[8:9]
	v_lshlrev_b32_e32 v18, 16, v128
	v_and_b32_e32 v19, 0xffff0000, v128
	v_pk_fma_f32 v[8:9], v[8:9], v[144:145], v[18:19]
	v_add_u32_e32 v14, 0x8000, v14
	v_cvt_pk_bf16_f32 v16, v8, v9
	global_store_dword v14, v16, s[8:9]
	v_lshlrev_b32_e32 v18, 16, v129
	v_and_b32_e32 v19, 0xffff0000, v129
	v_pk_fma_f32 v[8:9], v[8:9], v[146:147], v[18:19]
	v_add_u32_e32 v14, 0x8000, v14
	v_cvt_pk_bf16_f32 v16, v8, v9
	global_store_dword v14, v16, s[8:9]
	v_lshlrev_b32_e32 v18, 16, v130
	v_and_b32_e32 v19, 0xffff0000, v130
	v_pk_fma_f32 v[8:9], v[8:9], v[148:149], v[18:19]
	v_add_u32_e32 v14, 0x8000, v14
	v_cvt_pk_bf16_f32 v16, v8, v9
	global_store_dword v14, v16, s[8:9]
	v_lshlrev_b32_e32 v18, 16, v131
	v_and_b32_e32 v19, 0xffff0000, v131
	v_pk_fma_f32 v[8:9], v[8:9], v[150:151], v[18:19]
	v_add_u32_e32 v14, 0x8000, v14
	v_cvt_pk_bf16_f32 v16, v8, v9
	global_store_dword v14, v16, s[8:9]
	v_lshlrev_b32_e32 v18, 16, v132
	v_and_b32_e32 v19, 0xffff0000, v132
	v_pk_fma_f32 v[8:9], v[8:9], v[152:153], v[18:19]
	v_add_u32_e32 v14, 0x8000, v14
	v_cvt_pk_bf16_f32 v16, v8, v9
	global_store_dword v14, v16, s[8:9]
	v_lshlrev_b32_e32 v18, 16, v133
	v_and_b32_e32 v19, 0xffff0000, v133
	v_pk_fma_f32 v[8:9], v[8:9], v[154:155], v[18:19]
	v_add_u32_e32 v14, 0x8000, v14
	v_cvt_pk_bf16_f32 v16, v8, v9
	global_store_dword v14, v16, s[8:9]
	v_lshlrev_b32_e32 v18, 16, v134
	v_and_b32_e32 v19, 0xffff0000, v134
	v_pk_fma_f32 v[8:9], v[8:9], v[156:157], v[18:19]
	v_add_u32_e32 v14, 0x8000, v14
	v_cvt_pk_bf16_f32 v16, v8, v9
	global_store_dword v14, v16, s[8:9]
	v_lshlrev_b32_e32 v18, 16, v135
	v_and_b32_e32 v19, 0xffff0000, v135
	v_pk_fma_f32 v[8:9], v[8:9], v[158:159], v[18:19]
	v_add_u32_e32 v14, 0x8000, v14
	v_cvt_pk_bf16_f32 v16, v8, v9
	global_store_dword v14, v16, s[8:9]
	v_lshlrev_b32_e32 v18, 16, v136
	v_and_b32_e32 v19, 0xffff0000, v136
	v_pk_fma_f32 v[8:9], v[8:9], v[160:161], v[18:19]
	v_add_u32_e32 v14, 0x8000, v14
	v_cvt_pk_bf16_f32 v16, v8, v9
	global_store_dword v14, v16, s[8:9]
	v_lshlrev_b32_e32 v18, 16, v137
	v_and_b32_e32 v19, 0xffff0000, v137
	v_pk_fma_f32 v[8:9], v[8:9], v[162:163], v[18:19]
	v_add_u32_e32 v14, 0x8000, v14
	v_cvt_pk_bf16_f32 v16, v8, v9
	global_store_dword v14, v16, s[8:9]
	v_lshlrev_b32_e32 v18, 16, v138
	v_and_b32_e32 v19, 0xffff0000, v138
	v_pk_fma_f32 v[8:9], v[8:9], v[164:165], v[18:19]
	v_add_u32_e32 v14, 0x8000, v14
	v_cvt_pk_bf16_f32 v16, v8, v9
	global_store_dword v14, v16, s[8:9]
	v_lshlrev_b32_e32 v18, 16, v139
	v_and_b32_e32 v19, 0xffff0000, v139
	v_pk_fma_f32 v[8:9], v[8:9], v[166:167], v[18:19]
	v_add_u32_e32 v14, 0x8000, v14
	v_cvt_pk_bf16_f32 v16, v8, v9
	global_store_dword v14, v16, s[8:9]
	v_lshlrev_b32_e32 v18, 16, v140
	v_and_b32_e32 v19, 0xffff0000, v140
	v_pk_fma_f32 v[8:9], v[8:9], v[168:169], v[18:19]
	v_add_u32_e32 v14, 0x8000, v14
	v_cvt_pk_bf16_f32 v16, v8, v9
	global_store_dword v14, v16, s[8:9]
	v_lshlrev_b32_e32 v18, 16, v141
	v_and_b32_e32 v19, 0xffff0000, v141
	v_pk_fma_f32 v[8:9], v[8:9], v[170:171], v[18:19]
	v_add_u32_e32 v14, 0x8000, v14
	v_cvt_pk_bf16_f32 v16, v8, v9
	global_store_dword v14, v16, s[8:9]
	v_lshlrev_b32_e32 v18, 16, v142
	v_and_b32_e32 v19, 0xffff0000, v142
	v_pk_fma_f32 v[8:9], v[8:9], v[172:173], v[18:19]
	v_add_u32_e32 v14, 0x8000, v14
	v_cvt_pk_bf16_f32 v16, v8, v9
	global_store_dword v14, v16, s[8:9]
	v_lshlrev_b32_e32 v18, 16, v143
	v_and_b32_e32 v19, 0xffff0000, v143
	v_pk_fma_f32 v[8:9], v[8:9], v[174:175], v[18:19]
	v_add_u32_e32 v14, 0x8000, v14
	global_load_dword v48, v6, s[8:9]
	global_load_dwordx2 v[96:97], v12, s[10:11]
	v_add_u32_e32 v6, 0x8000, v6
	v_add_u32_e32 v12, 0x200, v12
	global_load_dword v49, v6, s[8:9]
	global_load_dwordx2 v[98:99], v12, s[10:11]
	v_add_u32_e32 v6, 0x8000, v6
	v_add_u32_e32 v12, 0x200, v12
	global_load_dword v50, v6, s[8:9]
	global_load_dwordx2 v[100:101], v12, s[10:11]
	v_add_u32_e32 v6, 0x8000, v6
	v_add_u32_e32 v12, 0x200, v12
	global_load_dword v51, v6, s[8:9]
	global_load_dwordx2 v[102:103], v12, s[10:11]
	v_add_u32_e32 v6, 0x8000, v6
	v_add_u32_e32 v12, 0x200, v12
	global_load_dword v52, v6, s[8:9]
	global_load_dwordx2 v[104:105], v12, s[10:11]
	v_add_u32_e32 v6, 0x8000, v6
	v_add_u32_e32 v12, 0x200, v12
	global_load_dword v53, v6, s[8:9]
	global_load_dwordx2 v[106:107], v12, s[10:11]
	v_add_u32_e32 v6, 0x8000, v6
	v_add_u32_e32 v12, 0x200, v12
	global_load_dword v54, v6, s[8:9]
	global_load_dwordx2 v[108:109], v12, s[10:11]
	v_add_u32_e32 v6, 0x8000, v6
	v_add_u32_e32 v12, 0x200, v12
	global_load_dword v55, v6, s[8:9]
	global_load_dwordx2 v[110:111], v12, s[10:11]
	v_add_u32_e32 v6, 0x8000, v6
	v_add_u32_e32 v12, 0x200, v12
	global_load_dword v56, v6, s[8:9]
	global_load_dwordx2 v[112:113], v12, s[10:11]
	v_add_u32_e32 v6, 0x8000, v6
	v_add_u32_e32 v12, 0x200, v12
	global_load_dword v57, v6, s[8:9]
	global_load_dwordx2 v[114:115], v12, s[10:11]
	v_add_u32_e32 v6, 0x8000, v6
	v_add_u32_e32 v12, 0x200, v12
	global_load_dword v58, v6, s[8:9]
	global_load_dwordx2 v[116:117], v12, s[10:11]
	v_add_u32_e32 v6, 0x8000, v6
	v_add_u32_e32 v12, 0x200, v12
	global_load_dword v59, v6, s[8:9]
	global_load_dwordx2 v[118:119], v12, s[10:11]
	v_add_u32_e32 v6, 0x8000, v6
	v_add_u32_e32 v12, 0x200, v12
	global_load_dword v60, v6, s[8:9]
	global_load_dwordx2 v[120:121], v12, s[10:11]
	v_add_u32_e32 v6, 0x8000, v6
	v_add_u32_e32 v12, 0x200, v12
	global_load_dword v61, v6, s[8:9]
	global_load_dwordx2 v[122:123], v12, s[10:11]
	v_add_u32_e32 v6, 0x8000, v6
	v_add_u32_e32 v12, 0x200, v12
	global_load_dword v62, v6, s[8:9]
	global_load_dwordx2 v[124:125], v12, s[10:11]
	v_add_u32_e32 v6, 0x8000, v6
	v_add_u32_e32 v12, 0x200, v12
	global_load_dword v63, v6, s[8:9]
	global_load_dwordx2 v[126:127], v12, s[10:11]
	v_add_u32_e32 v6, 0x8000, v6
	v_add_u32_e32 v12, 0x200, v12
	s_waitcnt vmcnt(48)
; __device__ __forceinline__ unsigned cvt_pk_bf16(float lo, float hi) { const f32x2cv v = {lo, hi}; const bf16x2cv b = __builtin_convertvector(v, bf16x2cv); return __builtin_bit_cast(unsigned, b); }
; __device__ __forceinline__ float bflo(unsigned w) { return __uint_as_float(w << 16); }
; __device__ __forceinline__ float bfhi(unsigned w) { return __uint_as_float(w & 0xffff0000u); }
; __device__ __forceinline__ void hgrn_pass2(Frame& F) {
;     ...
;     for (int item = F.vcu * 256 + F.tid; item < 8 * 128 * 64; item += F.G * 256) {
;         const int bh = item >> 13, rem = item & 8191;
;         unsigned* up = (unsigned*)((bf16*)F.out + (size_t)bh * 128 * 16384) + rem; const float2* dp = (const float2*)((const float*)(F.ws + WS_HD) + (size_t)bh * 128 * 128) + (rem & 63);
;         float s0 = 0.f, s1 = 0.f;
; #pragma unroll 32
;         for (int c = 0; c < 128; ++c) { const unsigned u = up[(size_t)c * 8192]; const float2 d = dp[c * 64];
;             up[(size_t)c * 8192] = cvt_pk_bf16(s0, s1);
;             s0 = d.x * s0 + bflo(u); s1 = d.y * s1 + bfhi(u); }
	v_cvt_pk_bf16_f32 v16, v8, v9
	global_store_dword v14, v16, s[8:9]
	v_lshlrev_b32_e32 v18, 16, v32
	v_and_b32_e32 v19, 0xffff0000, v32
	v_pk_fma_f32 v[8:9], v[8:9], v[64:65], v[18:19]
	v_add_u32_e32 v14, 0x8000, v14
	v_cvt_pk_bf16_f32 v16, v8, v9
	global_store_dword v14, v16, s[8:9]
	v_lshlrev_b32_e32 v18, 16, v33
	v_and_b32_e32 v19, 0xffff0000, v33
	v_pk_fma_f32 v[8:9], v[8:9], v[66:67], v[18:19]
	v_add_u32_e32 v14, 0x8000, v14
	v_cvt_pk_bf16_f32 v16, v8, v9
	global_store_dword v14, v16, s[8:9]
	v_lshlrev_b32_e32 v18, 16, v34
	v_and_b32_e32 v19, 0xffff0000, v34
	v_pk_fma_f32 v[8:9], v[8:9], v[68:69], v[18:19]
	v_add_u32_e32 v14, 0x8000, v14
	v_cvt_pk_bf16_f32 v16, v8, v9
	global_store_dword v14, v16, s[8:9]
	v_lshlrev_b32_e32 v18, 16, v35
	v_and_b32_e32 v19, 0xffff0000, v35
	v_pk_fma_f32 v[8:9], v[8:9], v[70:71], v[18:19]
	v_add_u32_e32 v14, 0x8000, v14
	v_cvt_pk_bf16_f32 v16, v8, v9
	global_store_dword v14, v16, s[8:9]
	v_lshlrev_b32_e32 v18, 16, v36
	v_and_b32_e32 v19, 0xffff0000, v36
	v_pk_fma_f32 v[8:9], v[8:9], v[72:73], v[18:19]
	v_add_u32_e32 v14, 0x8000, v14
	v_cvt_pk_bf16_f32 v16, v8, v9
	global_store_dword v14, v16, s[8:9]
	v_lshlrev_b32_e32 v18, 16, v37
	v_and_b32_e32 v19, 0xffff0000, v37
	v_pk_fma_f32 v[8:9], v[8:9], v[74:75], v[18:19]
	v_add_u32_e32 v14, 0x8000, v14
	v_cvt_pk_bf16_f32 v16, v8, v9
	global_store_dword v14, v16, s[8:9]
	v_lshlrev_b32_e32 v18, 16, v38
	v_and_b32_e32 v19, 0xffff0000, v38
	v_pk_fma_f32 v[8:9], v[8:9], v[76:77], v[18:19]
	v_add_u32_e32 v14, 0x8000, v14
	v_cvt_pk_bf16_f32 v16, v8, v9
	global_store_dword v14, v16, s[8:9]
	v_lshlrev_b32_e32 v18, 16, v39
	v_and_b32_e32 v19, 0xffff0000, v39
	v_pk_fma_f32 v[8:9], v[8:9], v[78:79], v[18:19]
	v_add_u32_e32 v14, 0x8000, v14
	v_cvt_pk_bf16_f32 v16, v8, v9
	global_store_dword v14, v16, s[8:9]
	v_lshlrev_b32_e32 v18, 16, v40
	v_and_b32_e32 v19, 0xffff0000, v40
	v_pk_fma_f32 v[8:9], v[8:9], v[80:81], v[18:19]
	v_add_u32_e32 v14, 0x8000, v14
	v_cvt_pk_bf16_f32 v16, v8, v9
	global_store_dword v14, v16, s[8:9]
	v_lshlrev_b32_e32 v18, 16, v41
	v_and_b32_e32 v19, 0xffff0000, v41
	v_pk_fma_f32 v[8:9], v[8:9], v[82:83], v[18:19]
	v_add_u32_e32 v14, 0x8000, v14
	v_cvt_pk_bf16_f32 v16, v8, v9
	global_store_dword v14, v16, s[8:9]
	v_lshlrev_b32_e32 v18, 16, v42
	v_and_b32_e32 v19, 0xffff0000, v42
	v_pk_fma_f32 v[8:9], v[8:9], v[84:85], v[18:19]
	v_add_u32_e32 v14, 0x8000, v14
	v_cvt_pk_bf16_f32 v16, v8, v9
	global_store_dword v14, v16, s[8:9]
	v_lshlrev_b32_e32 v18, 16, v43
	v_and_b32_e32 v19, 0xffff0000, v43
	v_pk_fma_f32 v[8:9], v[8:9], v[86:87], v[18:19]
	v_add_u32_e32 v14, 0x8000, v14
	v_cvt_pk_bf16_f32 v16, v8, v9
	global_store_dword v14, v16, s[8:9]
	v_lshlrev_b32_e32 v18, 16, v44
	v_and_b32_e32 v19, 0xffff0000, v44
	v_pk_fma_f32 v[8:9], v[8:9], v[88:89], v[18:19]
	v_add_u32_e32 v14, 0x8000, v14
	v_cvt_pk_bf16_f32 v16, v8, v9
	global_store_dword v14, v16, s[8:9]
	v_lshlrev_b32_e32 v18, 16, v45
	v_and_b32_e32 v19, 0xffff0000, v45
	v_pk_fma_f32 v[8:9], v[8:9], v[90:91], v[18:19]
	v_add_u32_e32 v14, 0x8000, v14
	v_cvt_pk_bf16_f32 v16, v8, v9
	global_store_dword v14, v16, s[8:9]
	v_lshlrev_b32_e32 v18, 16, v46
	v_and_b32_e32 v19, 0xffff0000, v46
	v_pk_fma_f32 v[8:9], v[8:9], v[92:93], v[18:19]
	v_add_u32_e32 v14, 0x8000, v14
	v_cvt_pk_bf16_f32 v16, v8, v9
	global_store_dword v14, v16, s[8:9]
	v_lshlrev_b32_e32 v18, 16, v47
	v_and_b32_e32 v19, 0xffff0000, v47
	v_pk_fma_f32 v[8:9], v[8:9], v[94:95], v[18:19]
	v_add_u32_e32 v14, 0x8000, v14
	global_load_dword v128, v6, s[8:9]
	global_load_dwordx2 v[144:145], v12, s[10:11]
	v_add_u32_e32 v6, 0x8000, v6
	v_add_u32_e32 v12, 0x200, v12
	global_load_dword v129, v6, s[8:9]
	global_load_dwordx2 v[146:147], v12, s[10:11]
	v_add_u32_e32 v6, 0x8000, v6
	v_add_u32_e32 v12, 0x200, v12
	global_load_dword v130, v6, s[8:9]
	global_load_dwordx2 v[148:149], v12, s[10:11]
	v_add_u32_e32 v6, 0x8000, v6
	v_add_u32_e32 v12, 0x200, v12
	global_load_dword v131, v6, s[8:9]
	global_load_dwordx2 v[150:151], v12, s[10:11]
	v_add_u32_e32 v6, 0x8000, v6
	v_add_u32_e32 v12, 0x200, v12
	global_load_dword v132, v6, s[8:9]
	global_load_dwordx2 v[152:153], v12, s[10:11]
	v_add_u32_e32 v6, 0x8000, v6
	v_add_u32_e32 v12, 0x200, v12
	global_load_dword v133, v6, s[8:9]
	global_load_dwordx2 v[154:155], v12, s[10:11]
	v_add_u32_e32 v6, 0x8000, v6
	v_add_u32_e32 v12, 0x200, v12
	global_load_dword v134, v6, s[8:9]
	global_load_dwordx2 v[156:157], v12, s[10:11]
	v_add_u32_e32 v6, 0x8000, v6
	v_add_u32_e32 v12, 0x200, v12
	global_load_dword v135, v6, s[8:9]
	global_load_dwordx2 v[158:159], v12, s[10:11]
	v_add_u32_e32 v6, 0x8000, v6
	v_add_u32_e32 v12, 0x200, v12
	global_load_dword v136, v6, s[8:9]
	global_load_dwordx2 v[160:161], v12, s[10:11]
	v_add_u32_e32 v6, 0x8000, v6
	v_add_u32_e32 v12, 0x200, v12
	global_load_dword v137, v6, s[8:9]
	global_load_dwordx2 v[162:163], v12, s[10:11]
	v_add_u32_e32 v6, 0x8000, v6
	v_add_u32_e32 v12, 0x200, v12
	global_load_dword v138, v6, s[8:9]
	global_load_dwordx2 v[164:165], v12, s[10:11]
	v_add_u32_e32 v6, 0x8000, v6
	v_add_u32_e32 v12, 0x200, v12
	global_load_dword v139, v6, s[8:9]
	global_load_dwordx2 v[166:167], v12, s[10:11]
	v_add_u32_e32 v6, 0x8000, v6
	v_add_u32_e32 v12, 0x200, v12
	global_load_dword v140, v6, s[8:9]
	global_load_dwordx2 v[168:169], v12, s[10:11]
	v_add_u32_e32 v6, 0x8000, v6
	v_add_u32_e32 v12, 0x200, v12
	global_load_dword v141, v6, s[8:9]
	global_load_dwordx2 v[170:171], v12, s[10:11]
	v_add_u32_e32 v6, 0x8000, v6
	v_add_u32_e32 v12, 0x200, v12
	global_load_dword v142, v6, s[8:9]
	global_load_dwordx2 v[172:173], v12, s[10:11]
	v_add_u32_e32 v6, 0x8000, v6
	v_add_u32_e32 v12, 0x200, v12
	global_load_dword v143, v6, s[8:9]
	global_load_dwordx2 v[174:175], v12, s[10:11]
	v_add_u32_e32 v6, 0x8000, v6
	v_add_u32_e32 v12, 0x200, v12
	s_waitcnt vmcnt(48)
; __device__ __forceinline__ unsigned cvt_pk_bf16(float lo, float hi) { const f32x2cv v = {lo, hi}; const bf16x2cv b = __builtin_convertvector(v, bf16x2cv); return __builtin_bit_cast(unsigned, b); }
; __device__ __forceinline__ float bflo(unsigned w) { return __uint_as_float(w << 16); }
; __device__ __forceinline__ float bfhi(unsigned w) { return __uint_as_float(w & 0xffff0000u); }
; __device__ __forceinline__ void hgrn_pass2(Frame& F) {
;     ...
;     for (int item = F.vcu * 256 + F.tid; item < 8 * 128 * 64; item += F.G * 256) {
;         const int bh = item >> 13, rem = item & 8191;
;         unsigned* up = (unsigned*)((bf16*)F.out + (size_t)bh * 128 * 16384) + rem; const float2* dp = (const float2*)((const float*)(F.ws + WS_HD) + (size_t)bh * 128 * 128) + (rem & 63);
;         float s0 = 0.f, s1 = 0.f;
; #pragma unroll 32
;         for (int c = 0; c < 128; ++c) { const unsigned u = up[(size_t)c * 8192]; const float2 d = dp[c * 64];
;             up[(size_t)c * 8192] = cvt_pk_bf16(s0, s1);
;             s0 = d.x * s0 + bflo(u); s1 = d.y * s1 + bfhi(u); }
	v_cvt_pk_bf16_f32 v16, v8, v9
	global_store_dword v14, v16, s[8:9]
	v_lshlrev_b32_e32 v18, 16, v48
	v_and_b32_e32 v19, 0xffff0000, v48
	v_pk_fma_f32 v[8:9], v[8:9], v[96:97], v[18:19]
	v_add_u32_e32 v14, 0x8000, v14
	v_cvt_pk_bf16_f32 v16, v8, v9
	global_store_dword v14, v16, s[8:9]
	v_lshlrev_b32_e32 v18, 16, v49
	v_and_b32_e32 v19, 0xffff0000, v49
	v_pk_fma_f32 v[8:9], v[8:9], v[98:99], v[18:19]
	v_add_u32_e32 v14, 0x8000, v14
	v_cvt_pk_bf16_f32 v16, v8, v9
	global_store_dword v14, v16, s[8:9]
	v_lshlrev_b32_e32 v18, 16, v50
	v_and_b32_e32 v19, 0xffff0000, v50
	v_pk_fma_f32 v[8:9], v[8:9], v[100:101], v[18:19]
	v_add_u32_e32 v14, 0x8000, v14
	v_cvt_pk_bf16_f32 v16, v8, v9
	global_store_dword v14, v16, s[8:9]
	v_lshlrev_b32_e32 v18, 16, v51
	v_and_b32_e32 v19, 0xffff0000, v51
	v_pk_fma_f32 v[8:9], v[8:9], v[102:103], v[18:19]
	v_add_u32_e32 v14, 0x8000, v14
	v_cvt_pk_bf16_f32 v16, v8, v9
	global_store_dword v14, v16, s[8:9]
	v_lshlrev_b32_e32 v18, 16, v52
	v_and_b32_e32 v19, 0xffff0000, v52
	v_pk_fma_f32 v[8:9], v[8:9], v[104:105], v[18:19]
	v_add_u32_e32 v14, 0x8000, v14
	v_cvt_pk_bf16_f32 v16, v8, v9
	global_store_dword v14, v16, s[8:9]
	v_lshlrev_b32_e32 v18, 16, v53
	v_and_b32_e32 v19, 0xffff0000, v53
	v_pk_fma_f32 v[8:9], v[8:9], v[106:107], v[18:19]
	v_add_u32_e32 v14, 0x8000, v14
	v_cvt_pk_bf16_f32 v16, v8, v9
	global_store_dword v14, v16, s[8:9]
	v_lshlrev_b32_e32 v18, 16, v54
	v_and_b32_e32 v19, 0xffff0000, v54
	v_pk_fma_f32 v[8:9], v[8:9], v[108:109], v[18:19]
	v_add_u32_e32 v14, 0x8000, v14
	v_cvt_pk_bf16_f32 v16, v8, v9
	global_store_dword v14, v16, s[8:9]
	v_lshlrev_b32_e32 v18, 16, v55
	v_and_b32_e32 v19, 0xffff0000, v55
	v_pk_fma_f32 v[8:9], v[8:9], v[110:111], v[18:19]
	v_add_u32_e32 v14, 0x8000, v14
	v_cvt_pk_bf16_f32 v16, v8, v9
	global_store_dword v14, v16, s[8:9]
	v_lshlrev_b32_e32 v18, 16, v56
	v_and_b32_e32 v19, 0xffff0000, v56
	v_pk_fma_f32 v[8:9], v[8:9], v[112:113], v[18:19]
	v_add_u32_e32 v14, 0x8000, v14
	v_cvt_pk_bf16_f32 v16, v8, v9
	global_store_dword v14, v16, s[8:9]
	v_lshlrev_b32_e32 v18, 16, v57
	v_and_b32_e32 v19, 0xffff0000, v57
	v_pk_fma_f32 v[8:9], v[8:9], v[114:115], v[18:19]
	v_add_u32_e32 v14, 0x8000, v14
	v_cvt_pk_bf16_f32 v16, v8, v9
	global_store_dword v14, v16, s[8:9]
	v_lshlrev_b32_e32 v18, 16, v58
	v_and_b32_e32 v19, 0xffff0000, v58
	v_pk_fma_f32 v[8:9], v[8:9], v[116:117], v[18:19]
	v_add_u32_e32 v14, 0x8000, v14
	v_cvt_pk_bf16_f32 v16, v8, v9
	global_store_dword v14, v16, s[8:9]
	v_lshlrev_b32_e32 v18, 16, v59
	v_and_b32_e32 v19, 0xffff0000, v59
	v_pk_fma_f32 v[8:9], v[8:9], v[118:119], v[18:19]
	v_add_u32_e32 v14, 0x8000, v14
	v_cvt_pk_bf16_f32 v16, v8, v9
	global_store_dword v14, v16, s[8:9]
	v_lshlrev_b32_e32 v18, 16, v60
	v_and_b32_e32 v19, 0xffff0000, v60
	v_pk_fma_f32 v[8:9], v[8:9], v[120:121], v[18:19]
	v_add_u32_e32 v14, 0x8000, v14
	v_cvt_pk_bf16_f32 v16, v8, v9
	global_store_dword v14, v16, s[8:9]
	v_lshlrev_b32_e32 v18, 16, v61
	v_and_b32_e32 v19, 0xffff0000, v61
	v_pk_fma_f32 v[8:9], v[8:9], v[122:123], v[18:19]
	v_add_u32_e32 v14, 0x8000, v14
	v_cvt_pk_bf16_f32 v16, v8, v9
	global_store_dword v14, v16, s[8:9]
	v_lshlrev_b32_e32 v18, 16, v62
	v_and_b32_e32 v19, 0xffff0000, v62
	v_pk_fma_f32 v[8:9], v[8:9], v[124:125], v[18:19]
	v_add_u32_e32 v14, 0x8000, v14
	v_cvt_pk_bf16_f32 v16, v8, v9
	global_store_dword v14, v16, s[8:9]
	v_lshlrev_b32_e32 v18, 16, v63
	v_and_b32_e32 v19, 0xffff0000, v63
	v_pk_fma_f32 v[8:9], v[8:9], v[126:127], v[18:19]
	v_add_u32_e32 v14, 0x8000, v14
	global_load_dword v32, v6, s[8:9]
	global_load_dwordx2 v[64:65], v12, s[10:11]
	v_add_u32_e32 v6, 0x8000, v6
	v_add_u32_e32 v12, 0x200, v12
	global_load_dword v33, v6, s[8:9]
	global_load_dwordx2 v[66:67], v12, s[10:11]
	v_add_u32_e32 v6, 0x8000, v6
	v_add_u32_e32 v12, 0x200, v12
	global_load_dword v34, v6, s[8:9]
	global_load_dwordx2 v[68:69], v12, s[10:11]
	v_add_u32_e32 v6, 0x8000, v6
	v_add_u32_e32 v12, 0x200, v12
	global_load_dword v35, v6, s[8:9]
	global_load_dwordx2 v[70:71], v12, s[10:11]
	v_add_u32_e32 v6, 0x8000, v6
	v_add_u32_e32 v12, 0x200, v12
	global_load_dword v36, v6, s[8:9]
	global_load_dwordx2 v[72:73], v12, s[10:11]
	v_add_u32_e32 v6, 0x8000, v6
	v_add_u32_e32 v12, 0x200, v12
	global_load_dword v37, v6, s[8:9]
	global_load_dwordx2 v[74:75], v12, s[10:11]
	v_add_u32_e32 v6, 0x8000, v6
	v_add_u32_e32 v12, 0x200, v12
	global_load_dword v38, v6, s[8:9]
	global_load_dwordx2 v[76:77], v12, s[10:11]
	v_add_u32_e32 v6, 0x8000, v6
	v_add_u32_e32 v12, 0x200, v12
	global_load_dword v39, v6, s[8:9]
	global_load_dwordx2 v[78:79], v12, s[10:11]
	v_add_u32_e32 v6, 0x8000, v6
	v_add_u32_e32 v12, 0x200, v12
	global_load_dword v40, v6, s[8:9]
	global_load_dwordx2 v[80:81], v12, s[10:11]
	v_add_u32_e32 v6, 0x8000, v6
	v_add_u32_e32 v12, 0x200, v12
	global_load_dword v41, v6, s[8:9]
	global_load_dwordx2 v[82:83], v12, s[10:11]
	v_add_u32_e32 v6, 0x8000, v6
	v_add_u32_e32 v12, 0x200, v12
	global_load_dword v42, v6, s[8:9]
	global_load_dwordx2 v[84:85], v12, s[10:11]
	v_add_u32_e32 v6, 0x8000, v6
	v_add_u32_e32 v12, 0x200, v12
	global_load_dword v43, v6, s[8:9]
	global_load_dwordx2 v[86:87], v12, s[10:11]
	v_add_u32_e32 v6, 0x8000, v6
	v_add_u32_e32 v12, 0x200, v12
	global_load_dword v44, v6, s[8:9]
	global_load_dwordx2 v[88:89], v12, s[10:11]
	v_add_u32_e32 v6, 0x8000, v6
	v_add_u32_e32 v12, 0x200, v12
	global_load_dword v45, v6, s[8:9]
	global_load_dwordx2 v[90:91], v12, s[10:11]
	v_add_u32_e32 v6, 0x8000, v6
	v_add_u32_e32 v12, 0x200, v12
	global_load_dword v46, v6, s[8:9]
	global_load_dwordx2 v[92:93], v12, s[10:11]
	v_add_u32_e32 v6, 0x8000, v6
	v_add_u32_e32 v12, 0x200, v12
	global_load_dword v47, v6, s[8:9]
	global_load_dwordx2 v[94:95], v12, s[10:11]
	v_add_u32_e32 v6, 0x8000, v6
	v_add_u32_e32 v12, 0x200, v12
	s_waitcnt vmcnt(48)
; __device__ __forceinline__ unsigned cvt_pk_bf16(float lo, float hi) { const f32x2cv v = {lo, hi}; const bf16x2cv b = __builtin_convertvector(v, bf16x2cv); return __builtin_bit_cast(unsigned, b); }
; __device__ __forceinline__ float bflo(unsigned w) { return __uint_as_float(w << 16); }
; __device__ __forceinline__ float bfhi(unsigned w) { return __uint_as_float(w & 0xffff0000u); }
; __device__ __forceinline__ void hgrn_pass2(Frame& F) {
;     ...
;     for (int item = F.vcu * 256 + F.tid; item < 8 * 128 * 64; item += F.G * 256) {
;         const int bh = item >> 13, rem = item & 8191;
;         unsigned* up = (unsigned*)((bf16*)F.out + (size_t)bh * 128 * 16384) + rem; const float2* dp = (const float2*)((const float*)(F.ws + WS_HD) + (size_t)bh * 128 * 128) + (rem & 63);
;         float s0 = 0.f, s1 = 0.f;
; #pragma unroll 32
;         for (int c = 0; c < 128; ++c) { const unsigned u = up[(size_t)c * 8192]; const float2 d = dp[c * 64];
;             up[(size_t)c * 8192] = cvt_pk_bf16(s0, s1);
;             s0 = d.x * s0 + bflo(u); s1 = d.y * s1 + bfhi(u); }
	v_cvt_pk_bf16_f32 v16, v8, v9
	global_store_dword v14, v16, s[8:9]
	v_lshlrev_b32_e32 v18, 16, v128
	v_and_b32_e32 v19, 0xffff0000, v128
	v_pk_fma_f32 v[8:9], v[8:9], v[144:145], v[18:19]
	v_add_u32_e32 v14, 0x8000, v14
	v_cvt_pk_bf16_f32 v16, v8, v9
	global_store_dword v14, v16, s[8:9]
	v_lshlrev_b32_e32 v18, 16, v129
	v_and_b32_e32 v19, 0xffff0000, v129
	v_pk_fma_f32 v[8:9], v[8:9], v[146:147], v[18:19]
	v_add_u32_e32 v14, 0x8000, v14
	v_cvt_pk_bf16_f32 v16, v8, v9
	global_store_dword v14, v16, s[8:9]
	v_lshlrev_b32_e32 v18, 16, v130
	v_and_b32_e32 v19, 0xffff0000, v130
	v_pk_fma_f32 v[8:9], v[8:9], v[148:149], v[18:19]
	v_add_u32_e32 v14, 0x8000, v14
	v_cvt_pk_bf16_f32 v16, v8, v9
	global_store_dword v14, v16, s[8:9]
	v_lshlrev_b32_e32 v18, 16, v131
	v_and_b32_e32 v19, 0xffff0000, v131
	v_pk_fma_f32 v[8:9], v[8:9], v[150:151], v[18:19]
	v_add_u32_e32 v14, 0x8000, v14
	v_cvt_pk_bf16_f32 v16, v8, v9
	global_store_dword v14, v16, s[8:9]
	v_lshlrev_b32_e32 v18, 16, v132
	v_and_b32_e32 v19, 0xffff0000, v132
	v_pk_fma_f32 v[8:9], v[8:9], v[152:153], v[18:19]
	v_add_u32_e32 v14, 0x8000, v14
	v_cvt_pk_bf16_f32 v16, v8, v9
	global_store_dword v14, v16, s[8:9]
	v_lshlrev_b32_e32 v18, 16, v133
	v_and_b32_e32 v19, 0xffff0000, v133
	v_pk_fma_f32 v[8:9], v[8:9], v[154:155], v[18:19]
	v_add_u32_e32 v14, 0x8000, v14
	v_cvt_pk_bf16_f32 v16, v8, v9
	global_store_dword v14, v16, s[8:9]
	v_lshlrev_b32_e32 v18, 16, v134
	v_and_b32_e32 v19, 0xffff0000, v134
	v_pk_fma_f32 v[8:9], v[8:9], v[156:157], v[18:19]
	v_add_u32_e32 v14, 0x8000, v14
	v_cvt_pk_bf16_f32 v16, v8, v9
	global_store_dword v14, v16, s[8:9]
	v_lshlrev_b32_e32 v18, 16, v135
	v_and_b32_e32 v19, 0xffff0000, v135
	v_pk_fma_f32 v[8:9], v[8:9], v[158:159], v[18:19]
	v_add_u32_e32 v14, 0x8000, v14
	v_cvt_pk_bf16_f32 v16, v8, v9
	global_store_dword v14, v16, s[8:9]
	v_lshlrev_b32_e32 v18, 16, v136
	v_and_b32_e32 v19, 0xffff0000, v136
	v_pk_fma_f32 v[8:9], v[8:9], v[160:161], v[18:19]
	v_add_u32_e32 v14, 0x8000, v14
	v_cvt_pk_bf16_f32 v16, v8, v9
	global_store_dword v14, v16, s[8:9]
	v_lshlrev_b32_e32 v18, 16, v137
	v_and_b32_e32 v19, 0xffff0000, v137
	v_pk_fma_f32 v[8:9], v[8:9], v[162:163], v[18:19]
	v_add_u32_e32 v14, 0x8000, v14
	v_cvt_pk_bf16_f32 v16, v8, v9
	global_store_dword v14, v16, s[8:9]
	v_lshlrev_b32_e32 v18, 16, v138
	v_and_b32_e32 v19, 0xffff0000, v138
	v_pk_fma_f32 v[8:9], v[8:9], v[164:165], v[18:19]
	v_add_u32_e32 v14, 0x8000, v14
	v_cvt_pk_bf16_f32 v16, v8, v9
	global_store_dword v14, v16, s[8:9]
	v_lshlrev_b32_e32 v18, 16, v139
	v_and_b32_e32 v19, 0xffff0000, v139
	v_pk_fma_f32 v[8:9], v[8:9], v[166:167], v[18:19]
	v_add_u32_e32 v14, 0x8000, v14
	v_cvt_pk_bf16_f32 v16, v8, v9
	global_store_dword v14, v16, s[8:9]
	v_lshlrev_b32_e32 v18, 16, v140
	v_and_b32_e32 v19, 0xffff0000, v140
	v_pk_fma_f32 v[8:9], v[8:9], v[168:169], v[18:19]
	v_add_u32_e32 v14, 0x8000, v14
	v_cvt_pk_bf16_f32 v16, v8, v9
	global_store_dword v14, v16, s[8:9]
	v_lshlrev_b32_e32 v18, 16, v141
	v_and_b32_e32 v19, 0xffff0000, v141
	v_pk_fma_f32 v[8:9], v[8:9], v[170:171], v[18:19]
	v_add_u32_e32 v14, 0x8000, v14
	v_cvt_pk_bf16_f32 v16, v8, v9
	global_store_dword v14, v16, s[8:9]
	v_lshlrev_b32_e32 v18, 16, v142
	v_and_b32_e32 v19, 0xffff0000, v142
	v_pk_fma_f32 v[8:9], v[8:9], v[172:173], v[18:19]
	v_add_u32_e32 v14, 0x8000, v14
	v_cvt_pk_bf16_f32 v16, v8, v9
	global_store_dword v14, v16, s[8:9]
	v_lshlrev_b32_e32 v18, 16, v143
	v_and_b32_e32 v19, 0xffff0000, v143
	v_pk_fma_f32 v[8:9], v[8:9], v[174:175], v[18:19]
	v_add_u32_e32 v14, 0x8000, v14
	global_load_dword v48, v6, s[8:9]
	global_load_dwordx2 v[96:97], v12, s[10:11]
	v_add_u32_e32 v6, 0x8000, v6
	v_add_u32_e32 v12, 0x200, v12
	global_load_dword v49, v6, s[8:9]
	global_load_dwordx2 v[98:99], v12, s[10:11]
	v_add_u32_e32 v6, 0x8000, v6
	v_add_u32_e32 v12, 0x200, v12
	global_load_dword v50, v6, s[8:9]
	global_load_dwordx2 v[100:101], v12, s[10:11]
	v_add_u32_e32 v6, 0x8000, v6
	v_add_u32_e32 v12, 0x200, v12
	global_load_dword v51, v6, s[8:9]
	global_load_dwordx2 v[102:103], v12, s[10:11]
	v_add_u32_e32 v6, 0x8000, v6
	v_add_u32_e32 v12, 0x200, v12
	global_load_dword v52, v6, s[8:9]
	global_load_dwordx2 v[104:105], v12, s[10:11]
	v_add_u32_e32 v6, 0x8000, v6
	v_add_u32_e32 v12, 0x200, v12
	global_load_dword v53, v6, s[8:9]
	global_load_dwordx2 v[106:107], v12, s[10:11]
	v_add_u32_e32 v6, 0x8000, v6
	v_add_u32_e32 v12, 0x200, v12
	global_load_dword v54, v6, s[8:9]
	global_load_dwordx2 v[108:109], v12, s[10:11]
	v_add_u32_e32 v6, 0x8000, v6
	v_add_u32_e32 v12, 0x200, v12
	global_load_dword v55, v6, s[8:9]
	global_load_dwordx2 v[110:111], v12, s[10:11]
	v_add_u32_e32 v6, 0x8000, v6
	v_add_u32_e32 v12, 0x200, v12
	global_load_dword v56, v6, s[8:9]
	global_load_dwordx2 v[112:113], v12, s[10:11]
	v_add_u32_e32 v6, 0x8000, v6
	v_add_u32_e32 v12, 0x200, v12
	global_load_dword v57, v6, s[8:9]
	global_load_dwordx2 v[114:115], v12, s[10:11]
	v_add_u32_e32 v6, 0x8000, v6
	v_add_u32_e32 v12, 0x200, v12
	global_load_dword v58, v6, s[8:9]
	global_load_dwordx2 v[116:117], v12, s[10:11]
	v_add_u32_e32 v6, 0x8000, v6
	v_add_u32_e32 v12, 0x200, v12
	global_load_dword v59, v6, s[8:9]
	global_load_dwordx2 v[118:119], v12, s[10:11]
	v_add_u32_e32 v6, 0x8000, v6
	v_add_u32_e32 v12, 0x200, v12
	global_load_dword v60, v6, s[8:9]
	global_load_dwordx2 v[120:121], v12, s[10:11]
	v_add_u32_e32 v6, 0x8000, v6
	v_add_u32_e32 v12, 0x200, v12
	global_load_dword v61, v6, s[8:9]
	global_load_dwordx2 v[122:123], v12, s[10:11]
	v_add_u32_e32 v6, 0x8000, v6
	v_add_u32_e32 v12, 0x200, v12
	global_load_dword v62, v6, s[8:9]
	global_load_dwordx2 v[124:125], v12, s[10:11]
	v_add_u32_e32 v6, 0x8000, v6
	v_add_u32_e32 v12, 0x200, v12
	global_load_dword v63, v6, s[8:9]
	global_load_dwordx2 v[126:127], v12, s[10:11]
	v_add_u32_e32 v6, 0x8000, v6
	v_add_u32_e32 v12, 0x200, v12
	s_waitcnt vmcnt(48)
; __device__ __forceinline__ unsigned cvt_pk_bf16(float lo, float hi) { const f32x2cv v = {lo, hi}; const bf16x2cv b = __builtin_convertvector(v, bf16x2cv); return __builtin_bit_cast(unsigned, b); }
; __device__ __forceinline__ float bflo(unsigned w) { return __uint_as_float(w << 16); }
; __device__ __forceinline__ float bfhi(unsigned w) { return __uint_as_float(w & 0xffff0000u); }
; __device__ __forceinline__ void hgrn_pass2(Frame& F) {
;     ...
;     for (int item = F.vcu * 256 + F.tid; item < 8 * 128 * 64; item += F.G * 256) {
;         const int bh = item >> 13, rem = item & 8191;
;         unsigned* up = (unsigned*)((bf16*)F.out + (size_t)bh * 128 * 16384) + rem; const float2* dp = (const float2*)((const float*)(F.ws + WS_HD) + (size_t)bh * 128 * 128) + (rem & 63);
;         float s0 = 0.f, s1 = 0.f;
; #pragma unroll 32
;         for (int c = 0; c < 128; ++c) { const unsigned u = up[(size_t)c * 8192]; const float2 d = dp[c * 64];
;             up[(size_t)c * 8192] = cvt_pk_bf16(s0, s1);
;             s0 = d.x * s0 + bflo(u); s1 = d.y * s1 + bfhi(u); }
	v_cvt_pk_bf16_f32 v16, v8, v9
	global_store_dword v14, v16, s[8:9]
	v_lshlrev_b32_e32 v18, 16, v32
	v_and_b32_e32 v19, 0xffff0000, v32
	v_pk_fma_f32 v[8:9], v[8:9], v[64:65], v[18:19]
	v_add_u32_e32 v14, 0x8000, v14
	v_cvt_pk_bf16_f32 v16, v8, v9
	global_store_dword v14, v16, s[8:9]
	v_lshlrev_b32_e32 v18, 16, v33
	v_and_b32_e32 v19, 0xffff0000, v33
	v_pk_fma_f32 v[8:9], v[8:9], v[66:67], v[18:19]
	v_add_u32_e32 v14, 0x8000, v14
	v_cvt_pk_bf16_f32 v16, v8, v9
	global_store_dword v14, v16, s[8:9]
	v_lshlrev_b32_e32 v18, 16, v34
	v_and_b32_e32 v19, 0xffff0000, v34
	v_pk_fma_f32 v[8:9], v[8:9], v[68:69], v[18:19]
	v_add_u32_e32 v14, 0x8000, v14
	v_cvt_pk_bf16_f32 v16, v8, v9
	global_store_dword v14, v16, s[8:9]
	v_lshlrev_b32_e32 v18, 16, v35
	v_and_b32_e32 v19, 0xffff0000, v35
	v_pk_fma_f32 v[8:9], v[8:9], v[70:71], v[18:19]
	v_add_u32_e32 v14, 0x8000, v14
	v_cvt_pk_bf16_f32 v16, v8, v9
	global_store_dword v14, v16, s[8:9]
	v_lshlrev_b32_e32 v18, 16, v36
	v_and_b32_e32 v19, 0xffff0000, v36
	v_pk_fma_f32 v[8:9], v[8:9], v[72:73], v[18:19]
	v_add_u32_e32 v14, 0x8000, v14
	v_cvt_pk_bf16_f32 v16, v8, v9
	global_store_dword v14, v16, s[8:9]
	v_lshlrev_b32_e32 v18, 16, v37
	v_and_b32_e32 v19, 0xffff0000, v37
	v_pk_fma_f32 v[8:9], v[8:9], v[74:75], v[18:19]
	v_add_u32_e32 v14, 0x8000, v14
	v_cvt_pk_bf16_f32 v16, v8, v9
	global_store_dword v14, v16, s[8:9]
	v_lshlrev_b32_e32 v18, 16, v38
	v_and_b32_e32 v19, 0xffff0000, v38
	v_pk_fma_f32 v[8:9], v[8:9], v[76:77], v[18:19]
	v_add_u32_e32 v14, 0x8000, v14
	v_cvt_pk_bf16_f32 v16, v8, v9
	global_store_dword v14, v16, s[8:9]
	v_lshlrev_b32_e32 v18, 16, v39
	v_and_b32_e32 v19, 0xffff0000, v39
	v_pk_fma_f32 v[8:9], v[8:9], v[78:79], v[18:19]
	v_add_u32_e32 v14, 0x8000, v14
	v_cvt_pk_bf16_f32 v16, v8, v9
	global_store_dword v14, v16, s[8:9]
	v_lshlrev_b32_e32 v18, 16, v40
	v_and_b32_e32 v19, 0xffff0000, v40
	v_pk_fma_f32 v[8:9], v[8:9], v[80:81], v[18:19]
	v_add_u32_e32 v14, 0x8000, v14
	v_cvt_pk_bf16_f32 v16, v8, v9
	global_store_dword v14, v16, s[8:9]
	v_lshlrev_b32_e32 v18, 16, v41
	v_and_b32_e32 v19, 0xffff0000, v41
	v_pk_fma_f32 v[8:9], v[8:9], v[82:83], v[18:19]
	v_add_u32_e32 v14, 0x8000, v14
	v_cvt_pk_bf16_f32 v16, v8, v9
	global_store_dword v14, v16, s[8:9]
	v_lshlrev_b32_e32 v18, 16, v42
	v_and_b32_e32 v19, 0xffff0000, v42
	v_pk_fma_f32 v[8:9], v[8:9], v[84:85], v[18:19]
	v_add_u32_e32 v14, 0x8000, v14
	v_cvt_pk_bf16_f32 v16, v8, v9
	global_store_dword v14, v16, s[8:9]
	v_lshlrev_b32_e32 v18, 16, v43
	v_and_b32_e32 v19, 0xffff0000, v43
	v_pk_fma_f32 v[8:9], v[8:9], v[86:87], v[18:19]
	v_add_u32_e32 v14, 0x8000, v14
	v_cvt_pk_bf16_f32 v16, v8, v9
	global_store_dword v14, v16, s[8:9]
	v_lshlrev_b32_e32 v18, 16, v44
	v_and_b32_e32 v19, 0xffff0000, v44
	v_pk_fma_f32 v[8:9], v[8:9], v[88:89], v[18:19]
	v_add_u32_e32 v14, 0x8000, v14
	v_cvt_pk_bf16_f32 v16, v8, v9
	global_store_dword v14, v16, s[8:9]
	v_lshlrev_b32_e32 v18, 16, v45
	v_and_b32_e32 v19, 0xffff0000, v45
	v_pk_fma_f32 v[8:9], v[8:9], v[90:91], v[18:19]
	v_add_u32_e32 v14, 0x8000, v14
	v_cvt_pk_bf16_f32 v16, v8, v9
	global_store_dword v14, v16, s[8:9]
	v_lshlrev_b32_e32 v18, 16, v46
	v_and_b32_e32 v19, 0xffff0000, v46
	v_pk_fma_f32 v[8:9], v[8:9], v[92:93], v[18:19]
	v_add_u32_e32 v14, 0x8000, v14
	v_cvt_pk_bf16_f32 v16, v8, v9
	global_store_dword v14, v16, s[8:9]
	v_lshlrev_b32_e32 v18, 16, v47
	v_and_b32_e32 v19, 0xffff0000, v47
	v_pk_fma_f32 v[8:9], v[8:9], v[94:95], v[18:19]
	v_add_u32_e32 v14, 0x8000, v14
	s_waitcnt vmcnt(16)
; __device__ __forceinline__ unsigned cvt_pk_bf16(float lo, float hi) { const f32x2cv v = {lo, hi}; const bf16x2cv b = __builtin_convertvector(v, bf16x2cv); return __builtin_bit_cast(unsigned, b); }
; __device__ __forceinline__ float bflo(unsigned w) { return __uint_as_float(w << 16); }
; __device__ __forceinline__ float bfhi(unsigned w) { return __uint_as_float(w & 0xffff0000u); }
; __device__ __forceinline__ void hgrn_pass2(Frame& F) {
;     ...
;     for (int item = F.vcu * 256 + F.tid; item < 8 * 128 * 64; item += F.G * 256) {
;         const int bh = item >> 13, rem = item & 8191;
;         unsigned* up = (unsigned*)((bf16*)F.out + (size_t)bh * 128 * 16384) + rem; const float2* dp = (const float2*)((const float*)(F.ws + WS_HD) + (size_t)bh * 128 * 128) + (rem & 63);
;         float s0 = 0.f, s1 = 0.f;
; #pragma unroll 32
;         for (int c = 0; c < 128; ++c) { const unsigned u = up[(size_t)c * 8192]; const float2 d = dp[c * 64];
;             up[(size_t)c * 8192] = cvt_pk_bf16(s0, s1);
;             s0 = d.x * s0 + bflo(u); s1 = d.y * s1 + bfhi(u); }
	v_cvt_pk_bf16_f32 v16, v8, v9
	global_store_dword v14, v16, s[8:9]
	v_lshlrev_b32_e32 v18, 16, v48
	v_and_b32_e32 v19, 0xffff0000, v48
	v_pk_fma_f32 v[8:9], v[8:9], v[96:97], v[18:19]
	v_add_u32_e32 v14, 0x8000, v14
	v_cvt_pk_bf16_f32 v16, v8, v9
	global_store_dword v14, v16, s[8:9]
	v_lshlrev_b32_e32 v18, 16, v49
	v_and_b32_e32 v19, 0xffff0000, v49
	v_pk_fma_f32 v[8:9], v[8:9], v[98:99], v[18:19]
	v_add_u32_e32 v14, 0x8000, v14
	v_cvt_pk_bf16_f32 v16, v8, v9
	global_store_dword v14, v16, s[8:9]
	v_lshlrev_b32_e32 v18, 16, v50
	v_and_b32_e32 v19, 0xffff0000, v50
	v_pk_fma_f32 v[8:9], v[8:9], v[100:101], v[18:19]
	v_add_u32_e32 v14, 0x8000, v14
	v_cvt_pk_bf16_f32 v16, v8, v9
	global_store_dword v14, v16, s[8:9]
	v_lshlrev_b32_e32 v18, 16, v51
	v_and_b32_e32 v19, 0xffff0000, v51
	v_pk_fma_f32 v[8:9], v[8:9], v[102:103], v[18:19]
	v_add_u32_e32 v14, 0x8000, v14
	v_cvt_pk_bf16_f32 v16, v8, v9
	global_store_dword v14, v16, s[8:9]
	v_lshlrev_b32_e32 v18, 16, v52
	v_and_b32_e32 v19, 0xffff0000, v52
	v_pk_fma_f32 v[8:9], v[8:9], v[104:105], v[18:19]
	v_add_u32_e32 v14, 0x8000, v14
	v_cvt_pk_bf16_f32 v16, v8, v9
	global_store_dword v14, v16, s[8:9]
	v_lshlrev_b32_e32 v18, 16, v53
	v_and_b32_e32 v19, 0xffff0000, v53
	v_pk_fma_f32 v[8:9], v[8:9], v[106:107], v[18:19]
	v_add_u32_e32 v14, 0x8000, v14
	v_cvt_pk_bf16_f32 v16, v8, v9
	global_store_dword v14, v16, s[8:9]
	v_lshlrev_b32_e32 v18, 16, v54
	v_and_b32_e32 v19, 0xffff0000, v54
	v_pk_fma_f32 v[8:9], v[8:9], v[108:109], v[18:19]
	v_add_u32_e32 v14, 0x8000, v14
	v_cvt_pk_bf16_f32 v16, v8, v9
	global_store_dword v14, v16, s[8:9]
	v_lshlrev_b32_e32 v18, 16, v55
	v_and_b32_e32 v19, 0xffff0000, v55
	v_pk_fma_f32 v[8:9], v[8:9], v[110:111], v[18:19]
	v_add_u32_e32 v14, 0x8000, v14
	v_cvt_pk_bf16_f32 v16, v8, v9
	global_store_dword v14, v16, s[8:9]
	v_lshlrev_b32_e32 v18, 16, v56
	v_and_b32_e32 v19, 0xffff0000, v56
	v_pk_fma_f32 v[8:9], v[8:9], v[112:113], v[18:19]
	v_add_u32_e32 v14, 0x8000, v14
	v_cvt_pk_bf16_f32 v16, v8, v9
	global_store_dword v14, v16, s[8:9]
	v_lshlrev_b32_e32 v18, 16, v57
	v_and_b32_e32 v19, 0xffff0000, v57
	v_pk_fma_f32 v[8:9], v[8:9], v[114:115], v[18:19]
	v_add_u32_e32 v14, 0x8000, v14
	v_cvt_pk_bf16_f32 v16, v8, v9
	global_store_dword v14, v16, s[8:9]
	v_lshlrev_b32_e32 v18, 16, v58
	v_and_b32_e32 v19, 0xffff0000, v58
	v_pk_fma_f32 v[8:9], v[8:9], v[116:117], v[18:19]
	v_add_u32_e32 v14, 0x8000, v14
	v_cvt_pk_bf16_f32 v16, v8, v9
	global_store_dword v14, v16, s[8:9]
	v_lshlrev_b32_e32 v18, 16, v59
	v_and_b32_e32 v19, 0xffff0000, v59
	v_pk_fma_f32 v[8:9], v[8:9], v[118:119], v[18:19]
	v_add_u32_e32 v14, 0x8000, v14
	v_cvt_pk_bf16_f32 v16, v8, v9
	global_store_dword v14, v16, s[8:9]
	v_lshlrev_b32_e32 v18, 16, v60
	v_and_b32_e32 v19, 0xffff0000, v60
	v_pk_fma_f32 v[8:9], v[8:9], v[120:121], v[18:19]
	v_add_u32_e32 v14, 0x8000, v14
	v_cvt_pk_bf16_f32 v16, v8, v9
	global_store_dword v14, v16, s[8:9]
	v_lshlrev_b32_e32 v18, 16, v61
	v_and_b32_e32 v19, 0xffff0000, v61
	v_pk_fma_f32 v[8:9], v[8:9], v[122:123], v[18:19]
	v_add_u32_e32 v14, 0x8000, v14
	v_cvt_pk_bf16_f32 v16, v8, v9
	global_store_dword v14, v16, s[8:9]
	v_lshlrev_b32_e32 v18, 16, v62
	v_and_b32_e32 v19, 0xffff0000, v62
	v_pk_fma_f32 v[8:9], v[8:9], v[124:125], v[18:19]
	v_add_u32_e32 v14, 0x8000, v14
	v_cvt_pk_bf16_f32 v16, v8, v9
	global_store_dword v14, v16, s[8:9]
	v_lshlrev_b32_e32 v18, 16, v63
	v_and_b32_e32 v19, 0xffff0000, v63
	v_pk_fma_f32 v[8:9], v[8:9], v[126:127], v[18:19]
	v_add_u32_e32 v14, 0x8000, v14
	v_add_u32_e32 v10, s1, v10
	s_mov_b32 s0, 0xffff
	v_cmp_lt_i32_e32 vcc, s0, v10
	s_or_b64 s[6:7], vcc, s[6:7]
	v_add_u16_e32 v11, s1, v11
	s_andn2_b64 exec, exec, s[6:7]
	s_cbranch_execnz .LBB0_621
